# combo15 + grid barrier: non-leader workgroups poll the top-level generation word directly (one memory round trip less per barrier), dead XGEN add removed
# baseline (speedup 1.0000x reference)
.LBB0_69:
	s_or_b64 exec, exec, s[10:11]
	v_cvt_f32_u32_e32 v4, v2
	s_waitcnt vmcnt(0)
	v_readfirstlane_b32 s3, v3
	v_sub_u32_e32 v3, 0, v2
	v_rcp_iflag_f32_e32 v4, v4
	v_add_u32_e32 v5, s3, v1
	v_mul_f32_e32 v4, 0x4f7ffffe, v4
	v_cvt_u32_f32_e32 v4, v4
	v_mul_lo_u32 v1, v3, v4
	v_mul_hi_u32 v1, v4, v1
	v_add_u32_e32 v1, v4, v1
	v_mul_hi_u32 v1, v5, v1
	v_mul_lo_u32 v3, v1, v2
	v_sub_u32_e32 v3, v5, v3
	v_add_u32_e32 v4, 1, v1
	v_cmp_ge_u32_e32 vcc, v3, v2
	s_nop 1
	v_cndmask_b32_e32 v1, v1, v4, vcc
	v_sub_u32_e32 v4, v3, v2
	v_cndmask_b32_e32 v3, v3, v4, vcc
	v_add_u32_e32 v4, 1, v1
	v_cmp_ge_u32_e32 vcc, v3, v2
	v_add_u32_e32 v3, 1, v5
	s_nop 0
	v_cndmask_b32_e32 v1, v1, v4, vcc
	v_mul_lo_u32 v4, v2, v1
	v_add_u32_e32 v2, v4, v2
	v_cmp_ne_u32_e32 vcc, v3, v2
	s_and_saveexec_b64 s[8:9], vcc
	s_xor_b64 s[8:9], exec, s[8:9]
	s_cbranch_execz .LBB0_83
	s_waitcnt lgkmcnt(0)
	s_add_u32 s14, s70, 0x3500
	s_addc_u32 s15, s71, 0
	v_mov_b32_e32 v0, 0
	global_load_dword v0, v0, s[14:15] sc1
	s_waitcnt vmcnt(0)
	v_cmp_eq_u32_e32 vcc, v0, v1
	s_and_saveexec_b64 s[10:11], vcc
	s_cbranch_execz .LBB0_82
	s_mov_b32 s3, 1
	s_mov_b64 s[16:17], 0
	v_mov_b32_e32 v0, 0
	s_branch .LBB0_73

.LBB0_100:
	s_or_b64 exec, exec, s[8:9]
	s_mov_b64 s[8:9], exec
	v_mbcnt_lo_u32_b32 v0, s8, 0
	v_mbcnt_hi_u32_b32 v0, s9, v0
	v_cmp_eq_u32_e32 vcc, 0, v0
	s_waitcnt vmcnt(0)
	buffer_inv sc1
	s_and_saveexec_b64 s[10:11], vcc
	s_cbranch_execz .LBB0_102
	s_bcnt1_i32_b64 s3, s[8:9]
	v_mov_b32_e32 v0, 0x2000
	v_mov_b32_e32 v1, s3
.LBB0_102:
	s_or_b64 exec, exec, s[10:11]
	s_waitcnt vmcnt(0)

.LBB0_136:
	s_or_b64 exec, exec, s[10:11]
	v_cvt_f32_u32_e32 v4, v2
	s_waitcnt vmcnt(0)
	v_readfirstlane_b32 s3, v3
	v_sub_u32_e32 v3, 0, v2
	v_rcp_iflag_f32_e32 v4, v4
	v_add_u32_e32 v5, s3, v1
	v_mul_f32_e32 v4, 0x4f7ffffe, v4
	v_cvt_u32_f32_e32 v4, v4
	v_mul_lo_u32 v1, v3, v4
	v_mul_hi_u32 v1, v4, v1
	v_add_u32_e32 v1, v4, v1
	v_mul_hi_u32 v1, v5, v1
	v_mul_lo_u32 v3, v1, v2
	v_sub_u32_e32 v3, v5, v3
	v_add_u32_e32 v4, 1, v1
	v_cmp_ge_u32_e32 vcc, v3, v2
	s_nop 1
	v_cndmask_b32_e32 v1, v1, v4, vcc
	v_sub_u32_e32 v4, v3, v2
	v_cndmask_b32_e32 v3, v3, v4, vcc
	v_add_u32_e32 v4, 1, v1
	v_cmp_ge_u32_e32 vcc, v3, v2
	v_add_u32_e32 v3, 1, v5
	s_nop 0
	v_cndmask_b32_e32 v1, v1, v4, vcc
	v_mul_lo_u32 v4, v2, v1
	v_add_u32_e32 v2, v4, v2
	v_cmp_ne_u32_e32 vcc, v3, v2
	s_and_saveexec_b64 s[8:9], vcc
	s_xor_b64 s[8:9], exec, s[8:9]
	s_cbranch_execz .LBB0_150
	s_waitcnt lgkmcnt(0)
	s_add_u32 s16, s70, 0x3500
	s_addc_u32 s17, s71, 0
	v_mov_b32_e32 v0, 0
	global_load_dword v0, v0, s[16:17] sc1
	s_waitcnt vmcnt(0)
	v_cmp_eq_u32_e32 vcc, v0, v1
	s_and_saveexec_b64 s[10:11], vcc
	s_cbranch_execz .LBB0_149
	s_mov_b32 s3, 1
	s_mov_b64 s[20:21], 0
	v_mov_b32_e32 v0, 0
	s_branch .LBB0_140

.LBB0_167:
	s_or_b64 exec, exec, s[8:9]
	s_mov_b64 s[8:9], exec
	v_mbcnt_lo_u32_b32 v0, s8, 0
	v_mbcnt_hi_u32_b32 v0, s9, v0
	v_cmp_eq_u32_e32 vcc, 0, v0
	s_waitcnt vmcnt(0)
	buffer_inv sc1
	s_and_saveexec_b64 s[10:11], vcc
	s_cbranch_execz .LBB0_169
	s_bcnt1_i32_b64 s3, s[8:9]
	v_mov_b32_e32 v0, 0x2000
	v_mov_b32_e32 v1, s3
.LBB0_169:
	s_or_b64 exec, exec, s[10:11]
	s_waitcnt vmcnt(0)

.LBB0_1096:
	s_or_b64 exec, exec, s[10:11]
	v_cvt_f32_u32_e32 v4, v2
	s_waitcnt vmcnt(0)
	v_readfirstlane_b32 s3, v3
	v_sub_u32_e32 v3, 0, v2
	v_rcp_iflag_f32_e32 v4, v4
	v_add_u32_e32 v5, s3, v1
	v_mul_f32_e32 v4, 0x4f7ffffe, v4
	v_cvt_u32_f32_e32 v4, v4
	v_mul_lo_u32 v1, v3, v4
	v_mul_hi_u32 v1, v4, v1
	v_add_u32_e32 v1, v4, v1
	v_mul_hi_u32 v1, v5, v1
	v_mul_lo_u32 v3, v1, v2
	v_sub_u32_e32 v3, v5, v3
	v_add_u32_e32 v4, 1, v1
	v_cmp_ge_u32_e32 vcc, v3, v2
	s_nop 1
	v_cndmask_b32_e32 v1, v1, v4, vcc
	v_sub_u32_e32 v4, v3, v2
	v_cndmask_b32_e32 v3, v3, v4, vcc
	v_add_u32_e32 v4, 1, v1
	v_cmp_ge_u32_e32 vcc, v3, v2
	v_add_u32_e32 v3, 1, v5
	s_nop 0
	v_cndmask_b32_e32 v1, v1, v4, vcc
	v_mul_lo_u32 v4, v2, v1
	v_add_u32_e32 v2, v4, v2
	v_cmp_ne_u32_e32 vcc, v3, v2
	s_and_saveexec_b64 s[8:9], vcc
	s_xor_b64 s[8:9], exec, s[8:9]
	s_cbranch_execz .LBB0_1110
	s_waitcnt lgkmcnt(0)
	s_add_u32 s12, s70, 0x3500
	s_addc_u32 s13, s71, 0
	v_mov_b32_e32 v0, 0
	global_load_dword v0, v0, s[12:13] sc1
	s_waitcnt vmcnt(0)
	v_cmp_eq_u32_e32 vcc, v0, v1
	s_and_saveexec_b64 s[10:11], vcc
	s_cbranch_execz .LBB0_1109
	s_mov_b32 s3, 1
	s_mov_b64 s[14:15], 0
	v_mov_b32_e32 v0, 0
	s_branch .LBB0_1100

.LBB0_1127:
	s_or_b64 exec, exec, s[8:9]
	s_mov_b64 s[8:9], exec
	v_mbcnt_lo_u32_b32 v0, s8, 0
	v_mbcnt_hi_u32_b32 v0, s9, v0
	v_cmp_eq_u32_e32 vcc, 0, v0
	s_waitcnt vmcnt(0)
	buffer_inv sc1
	s_and_saveexec_b64 s[10:11], vcc
	s_cbranch_execz .LBB0_1129
	s_bcnt1_i32_b64 s3, s[8:9]
	v_mov_b32_e32 v0, 0x2000
	v_mov_b32_e32 v1, s3
.LBB0_1129:
	s_or_b64 exec, exec, s[10:11]
	s_waitcnt vmcnt(0)

.LBB0_1597:
	s_or_b64 exec, exec, s[8:9]
	s_mov_b64 s[8:9], exec
	v_mbcnt_lo_u32_b32 v0, s8, 0
	v_mbcnt_hi_u32_b32 v0, s9, v0
	v_cmp_eq_u32_e32 vcc, 0, v0
	s_waitcnt vmcnt(0)
	buffer_inv sc1
	s_and_saveexec_b64 s[10:11], vcc
	s_cbranch_execz .LBB0_1599
	s_bcnt1_i32_b64 s3, s[8:9]
	v_mov_b32_e32 v0, 0x2000
	v_mov_b32_e32 v1, s3
.LBB0_1599:
	s_or_b64 exec, exec, s[10:11]
	s_waitcnt vmcnt(0)

.LBB0_1686:
	s_or_b64 exec, exec, s[12:13]
	v_cvt_f32_u32_e32 v4, v2
	s_waitcnt vmcnt(0)
	v_readfirstlane_b32 s3, v3
	v_sub_u32_e32 v3, 0, v2
	v_rcp_iflag_f32_e32 v4, v4
	v_add_u32_e32 v5, s3, v1
	v_mul_f32_e32 v4, 0x4f7ffffe, v4
	v_cvt_u32_f32_e32 v4, v4
	v_mul_lo_u32 v1, v3, v4
	v_mul_hi_u32 v1, v4, v1
	v_add_u32_e32 v1, v4, v1
	v_mul_hi_u32 v1, v5, v1
	v_mul_lo_u32 v3, v1, v2
	v_sub_u32_e32 v3, v5, v3
	v_add_u32_e32 v4, 1, v1
	v_cmp_ge_u32_e32 vcc, v3, v2
	s_nop 1
	v_cndmask_b32_e32 v1, v1, v4, vcc
	v_sub_u32_e32 v4, v3, v2
	v_cndmask_b32_e32 v3, v3, v4, vcc
	v_add_u32_e32 v4, 1, v1
	v_cmp_ge_u32_e32 vcc, v3, v2
	v_add_u32_e32 v3, 1, v5
	s_nop 0
	v_cndmask_b32_e32 v1, v1, v4, vcc
	v_mul_lo_u32 v4, v2, v1
	v_add_u32_e32 v2, v4, v2
	v_cmp_ne_u32_e32 vcc, v3, v2
	s_and_saveexec_b64 s[10:11], vcc
	s_xor_b64 s[10:11], exec, s[10:11]
	s_cbranch_execz .LBB0_1700
	s_waitcnt lgkmcnt(0)
	s_add_u32 s14, s70, 0x3500
	s_addc_u32 s15, s71, 0
	v_mov_b32_e32 v0, 0
	global_load_dword v0, v0, s[14:15] sc1
	s_waitcnt vmcnt(0)
	v_cmp_eq_u32_e32 vcc, v0, v1
	s_and_saveexec_b64 s[12:13], vcc
	s_cbranch_execz .LBB0_1699
	s_mov_b32 s3, 1
	s_mov_b64 s[16:17], 0
	v_mov_b32_e32 v0, 0
	s_branch .LBB0_1690

.LBB0_1717:
	s_or_b64 exec, exec, s[10:11]
	s_mov_b64 s[10:11], exec
	v_mbcnt_lo_u32_b32 v0, s10, 0
	v_mbcnt_hi_u32_b32 v0, s11, v0
	v_cmp_eq_u32_e32 vcc, 0, v0
	s_waitcnt vmcnt(0)
	buffer_inv sc1
	s_and_saveexec_b64 s[12:13], vcc
	s_cbranch_execz .LBB0_1719
	s_bcnt1_i32_b64 s3, s[10:11]
	v_mov_b32_e32 v0, 0x2000
	v_mov_b32_e32 v1, s3
.LBB0_1719:
	s_or_b64 exec, exec, s[12:13]
	s_waitcnt vmcnt(0)
